# K-loops: removed the back-to-back s_setprio 0/1 pair between the two MFMA blocks of each segment
# speedup vs baseline: 1.0053x; 1.0031x over previous
; #define PG8_STAGE(bufoff, gbase, voff) do { _Pragma("unroll") for (int _i = 0; _i < 2; ++_i) \
;         __builtin_amdgcn_global_load_lds((const unsigned*)((const char*)(gbase) + (voff)[_i]), (PG8_LAS unsigned*)(lds + (bufoff) + ldsw + _i * 8192), 16, 0, 0); } while (0)
; #define PG8_LDA(dst, b, h) do { _Pragma("unroll") for (int m = 0; m < 4; ++m) _Pragma("unroll") for (int k = 0; k < 2; ++k) dst[m][k] = *(const PG8_LAS bf16x8*)(lds + PG8_SA(b, h) + aoff + m * 2048 + k * 1024); } while (0)
; #define PG8_LDB(dst, b, h) do { _Pragma("unroll") for (int n = 0; n < 2; ++n) _Pragma("unroll") for (int k = 0; k < 2; ++k) dst[n][k] = *(const PG8_LAS bf16x8*)(lds + PG8_SB(b, h) + boff + n * 2048 + k * 1024); } while (0)
; #define PG8_MMA(ai, bj, At, Bt) do { __builtin_amdgcn_s_setprio(1); _Pragma("unroll") for (int m = 0; m < 4; ++m) _Pragma("unroll") for (int n = 0; n < 2; ++n) _Pragma("unroll") for (int k = 0; k < 2; ++k) \
;         acc[ai][bj][m][n] = __builtin_amdgcn_mfma_f32_16x16x32_bf16(Bt[n][k], At[m][k], acc[ai][bj][m][n], 0, 0, 0); __builtin_amdgcn_s_setprio(0); } while (0)
; #define PG8_WAIT_V(n) asm volatile("s_waitcnt vmcnt(" #n ")" ::: "memory")
; #define PG8_WAIT_L(n) asm volatile("s_waitcnt lgkmcnt(" #n ")" ::: "memory")
; template <class Epi, class Sched, bool ALIGN_EPI = false, bool SP2 = false>
; __device__ __forceinline__ void gemm_phase(PG8_LAS unsigned char* lds, const Gemm g, const Sched& S, const Epi& E) {
;     ...
;             const bool last = (t == nt - 2);
;             const char* a1 = cA + (size_t)(t + 1) * kstep;
;             const char* a2 = last ? nA : cA + (size_t)(t + 2) * kstep; const char* b2 = last ? nB : cB + (size_t)(t + 2) * kstep;
;             const char* a3 = a2 + kstep; const char* b3 = b2 + kstep;
;             if (last && has_next) S.a_ready(nxt);
;             if constexpr (SP2) {
;             PG8_LDB(B0, 0, 0); PG8_LDB(B1, 0, 1); PG8_SCHED; PG8_LDA(At, 0, 0); PG8_STAGE(PG8_SA(1, 1), a1 + hstep, voffA);
;             PG8_WAIT_V(8); PG8_WAIT_L(0); PG8_BAR; PG8_MMA(0, 0, At, B0); PG8_MMA(0, 1, At, B1); PG8_BAR; PG8_SCHED;
;             PG8_LDA(At, 0, 1); PG8_STAGE(PG8_SB(0, 0), b2, voffB); PG8_STAGE(PG8_SB(0, 1), b2 + hstep, voffB); PG8_STAGE(PG8_SA(0, 0), a2, voffA);
;             PG8_WAIT_V(8); PG8_WAIT_L(0); PG8_BAR; PG8_MMA(1, 0, At, B0); PG8_MMA(1, 1, At, B1); PG8_BAR; PG8_SCHED;
.LBB0_236:
	s_add_u32 s76, s86, 0xfffc0080
	s_addc_u32 s77, s87, -1
	s_add_i32 s80, 0, 0x10000
	s_cmp_eq_u32 s75, 12
	s_cselect_b32 s91, s66, s77
	s_cselect_b32 s90, s67, s76
	s_cselect_b32 s89, s39, s71
	s_cselect_b32 s88, s68, s69
	s_add_i32 s81, 0, 0x14000
	v_add_u32_e32 v154, s80, v176
	v_add_u32_e32 v186, s81, v176
	ds_read_b128 v[48:51], v154
	ds_read_b128 v[60:63], v154 offset:1024
	ds_read_b128 v[138:141], v154 offset:2048
	ds_read_b128 v[154:157], v154 offset:3072
	ds_read_b128 v[158:161], v186
	ds_read_b128 v[178:181], v186 offset:1024
	ds_read_b128 v[182:185], v186 offset:2048
	ds_read_b128 v[186:189], v186 offset:3072
	v_lshl_add_u64 v[194:195], s[86:87], 0, v[150:151]
	s_add_i32 m0, s15, 0xc000
	ds_read_b128 v[190:193], v177
	ds_read_b128 v[212:215], v177 offset:1024
	ds_read_b128 v[216:219], v177 offset:2048
	ds_read_b128 v[220:223], v177 offset:3072
	ds_read_b128 v[224:227], v177 offset:4096
	ds_read_b128 v[228:231], v177 offset:5120
	ds_read_b128 v[232:235], v177 offset:6144
	ds_read_b128 v[236:239], v177 offset:7168
	global_load_lds_dwordx4 v[194:195], off
	v_lshl_add_u64 v[194:195], s[86:87], 0, v[152:153]
	s_add_i32 m0, s15, 0xe000
	s_nop 0
	global_load_lds_dwordx4 v[194:195], off
	s_waitcnt vmcnt(8)
	s_waitcnt lgkmcnt(0)
	s_barrier
	s_setprio 1
	s_waitcnt lgkmcnt(0)
	v_mfma_f32_16x16x32_bf16 v[134:137], v[48:51], v[190:193], v[134:137]
	v_mfma_f32_16x16x32_bf16 v[126:129], v[138:141], v[190:193], v[126:129]
	v_mfma_f32_16x16x32_bf16 v[110:113], v[138:141], v[216:219], v[110:113]
	v_mfma_f32_16x16x32_bf16 v[118:121], v[48:51], v[216:219], v[118:121]
	v_mfma_f32_16x16x32_bf16 v[102:105], v[48:51], v[224:227], v[102:105]
	v_mfma_f32_16x16x32_bf16 v[94:97], v[138:141], v[224:227], v[94:97]
	v_mfma_f32_16x16x32_bf16 v[76:79], v[138:141], v[232:235], v[76:79]
	v_mfma_f32_16x16x32_bf16 v[86:89], v[48:51], v[232:235], v[86:89]
	v_mfma_f32_16x16x32_bf16 v[134:137], v[60:63], v[212:215], v[134:137]
	v_mfma_f32_16x16x32_bf16 v[126:129], v[154:157], v[212:215], v[126:129]
	v_mfma_f32_16x16x32_bf16 v[110:113], v[154:157], v[220:223], v[110:113]
	v_mfma_f32_16x16x32_bf16 v[118:121], v[60:63], v[220:223], v[118:121]
	v_mfma_f32_16x16x32_bf16 v[102:105], v[60:63], v[228:231], v[102:105]
	v_mfma_f32_16x16x32_bf16 v[94:97], v[154:157], v[228:231], v[94:97]
	v_mfma_f32_16x16x32_bf16 v[76:79], v[154:157], v[236:239], v[76:79]
	v_mfma_f32_16x16x32_bf16 v[86:89], v[60:63], v[236:239], v[86:89]
	v_mfma_f32_16x16x32_bf16 v[130:133], v[158:161], v[190:193], v[130:133]
	v_mfma_f32_16x16x32_bf16 v[122:125], v[182:185], v[190:193], v[122:125]
	v_mfma_f32_16x16x32_bf16 v[106:109], v[182:185], v[216:219], v[106:109]
	v_mfma_f32_16x16x32_bf16 v[114:117], v[158:161], v[216:219], v[114:117]
	v_mfma_f32_16x16x32_bf16 v[98:101], v[158:161], v[224:227], v[98:101]
	v_mfma_f32_16x16x32_bf16 v[90:93], v[182:185], v[224:227], v[90:93]
	v_mfma_f32_16x16x32_bf16 v[72:75], v[182:185], v[232:235], v[72:75]
	v_mfma_f32_16x16x32_bf16 v[82:85], v[158:161], v[232:235], v[82:85]
	v_mfma_f32_16x16x32_bf16 v[130:133], v[178:181], v[212:215], v[130:133]
	v_mfma_f32_16x16x32_bf16 v[122:125], v[186:189], v[212:215], v[122:125]
	v_mfma_f32_16x16x32_bf16 v[106:109], v[186:189], v[220:223], v[106:109]
	v_mfma_f32_16x16x32_bf16 v[114:117], v[178:181], v[220:223], v[114:117]
	v_mfma_f32_16x16x32_bf16 v[98:101], v[178:181], v[228:231], v[98:101]
	v_mfma_f32_16x16x32_bf16 v[90:93], v[186:189], v[228:231], v[90:93]
	v_mfma_f32_16x16x32_bf16 v[72:75], v[186:189], v[236:239], v[72:75]
	v_mfma_f32_16x16x32_bf16 v[82:85], v[178:181], v[236:239], v[82:85]
	s_setprio 0
	s_barrier
	s_add_i32 s76, s80, s13
	v_lshl_add_u64 v[194:195], s[88:89], 0, v[144:145]
	s_mov_b32 m0, s76
	ds_read_b128 v[190:193], v177 offset:16384
	ds_read_b128 v[212:215], v177 offset:17408
	ds_read_b128 v[216:219], v177 offset:18432
	ds_read_b128 v[220:223], v177 offset:19456
	ds_read_b128 v[224:227], v177 offset:20480
	ds_read_b128 v[228:231], v177 offset:21504
	ds_read_b128 v[232:235], v177 offset:22528
	ds_read_b128 v[236:239], v177 offset:23552
	global_load_lds_dwordx4 v[194:195], off
	s_add_i32 m0, s76, 0x2000
	s_add_u32 s76, s88, 0x40000
	v_lshl_add_u64 v[240:241], s[88:89], 0, v[148:149]
	s_addc_u32 s77, s89, 0
	s_add_i32 s80, s81, s13
	global_load_lds_dwordx4 v[240:241], off
	v_lshl_add_u64 v[242:243], s[76:77], 0, v[144:145]
	s_mov_b32 m0, s80
	v_lshl_add_u64 v[244:245], s[90:91], 0, v[146:147]
	global_load_lds_dwordx4 v[242:243], off
	v_lshl_add_u64 v[242:243], s[76:77], 0, v[148:149]
	s_add_i32 m0, s80, 0x2000
	s_nop 0
	global_load_lds_dwordx4 v[242:243], off
	v_lshl_add_u64 v[242:243], s[90:91], 0, v[142:143]
	s_mov_b32 m0, s15
	s_nop 0
	global_load_lds_dwordx4 v[242:243], off
	s_mov_b32 m0, s16
	s_nop 0
	global_load_lds_dwordx4 v[244:245], off
	s_waitcnt vmcnt(8)
	s_waitcnt lgkmcnt(0)
	s_barrier
; #define PG8_STAGE(bufoff, gbase, voff) do { _Pragma("unroll") for (int _i = 0; _i < 2; ++_i) \
;         __builtin_amdgcn_global_load_lds((const unsigned*)((const char*)(gbase) + (voff)[_i]), (PG8_LAS unsigned*)(lds + (bufoff) + ldsw + _i * 8192), 16, 0, 0); } while (0)
; #define PG8_LDA(dst, b, h) do { _Pragma("unroll") for (int m = 0; m < 4; ++m) _Pragma("unroll") for (int k = 0; k < 2; ++k) dst[m][k] = *(const PG8_LAS bf16x8*)(lds + PG8_SA(b, h) + aoff + m * 2048 + k * 1024); } while (0)
; #define PG8_LDB(dst, b, h) do { _Pragma("unroll") for (int n = 0; n < 2; ++n) _Pragma("unroll") for (int k = 0; k < 2; ++k) dst[n][k] = *(const PG8_LAS bf16x8*)(lds + PG8_SB(b, h) + boff + n * 2048 + k * 1024); } while (0)
; #define PG8_MMA(ai, bj, At, Bt) do { __builtin_amdgcn_s_setprio(1); _Pragma("unroll") for (int m = 0; m < 4; ++m) _Pragma("unroll") for (int n = 0; n < 2; ++n) _Pragma("unroll") for (int k = 0; k < 2; ++k) \
;         acc[ai][bj][m][n] = __builtin_amdgcn_mfma_f32_16x16x32_bf16(Bt[n][k], At[m][k], acc[ai][bj][m][n], 0, 0, 0); __builtin_amdgcn_s_setprio(0); } while (0)
; #define PG8_WAIT_V(n) asm volatile("s_waitcnt vmcnt(" #n ")" ::: "memory")
; #define PG8_WAIT_L(n) asm volatile("s_waitcnt lgkmcnt(" #n ")" ::: "memory")
; #define PG8_BAR __builtin_amdgcn_s_barrier()
; #define PG8_SCHED __builtin_amdgcn_sched_barrier(0)
; template <class Epi, class Sched, bool ALIGN_EPI = false, bool SP2 = false>
; __device__ __forceinline__ void gemm_phase(PG8_LAS unsigned char* lds, const Gemm g, const Sched& S, const Epi& E) {
;     ...
;             PG8_WAIT_V(8); PG8_WAIT_L(0); PG8_BAR; PG8_MMA(1, 0, At, B0); PG8_MMA(1, 1, At, B1); PG8_BAR; PG8_SCHED;
;             PG8_LDB(B0, 1, 0); PG8_LDB(B1, 1, 1); PG8_SCHED; PG8_LDA(At, 1, 0); PG8_STAGE(PG8_SA(0, 1), a2 + hstep, voffA);
;             PG8_WAIT_V(8); PG8_WAIT_L(0); PG8_BAR; PG8_MMA(0, 0, At, B0); PG8_MMA(0, 1, At, B1); PG8_BAR; PG8_SCHED;
	s_setprio 1
	s_waitcnt lgkmcnt(0)
	v_mfma_f32_16x16x32_bf16 v[68:71], v[48:51], v[190:193], v[68:71]
	v_mfma_f32_16x16x32_bf16 v[56:59], v[138:141], v[190:193], v[56:59]
	v_mfma_f32_16x16x32_bf16 v[36:39], v[138:141], v[216:219], v[36:39]
	v_mfma_f32_16x16x32_bf16 v[44:47], v[48:51], v[216:219], v[44:47]
	v_mfma_f32_16x16x32_bf16 v[28:31], v[48:51], v[224:227], v[28:31]
	v_mfma_f32_16x16x32_bf16 v[20:23], v[138:141], v[224:227], v[20:23]
	v_mfma_f32_16x16x32_bf16 v[4:7], v[138:141], v[232:235], v[4:7]
	v_mfma_f32_16x16x32_bf16 v[12:15], v[48:51], v[232:235], v[12:15]
	v_mfma_f32_16x16x32_bf16 v[68:71], v[60:63], v[212:215], v[68:71]
	v_mfma_f32_16x16x32_bf16 v[56:59], v[154:157], v[212:215], v[56:59]
	v_mfma_f32_16x16x32_bf16 v[36:39], v[154:157], v[220:223], v[36:39]
	v_mfma_f32_16x16x32_bf16 v[44:47], v[60:63], v[220:223], v[44:47]
	v_mfma_f32_16x16x32_bf16 v[28:31], v[60:63], v[228:231], v[28:31]
	v_mfma_f32_16x16x32_bf16 v[20:23], v[154:157], v[228:231], v[20:23]
	v_mfma_f32_16x16x32_bf16 v[4:7], v[154:157], v[236:239], v[4:7]
	v_mfma_f32_16x16x32_bf16 v[12:15], v[60:63], v[236:239], v[12:15]
	v_mfma_f32_16x16x32_bf16 v[52:55], v[182:185], v[190:193], v[52:55]
	v_mfma_f32_16x16x32_bf16 v[40:43], v[158:161], v[216:219], v[40:43]
	v_mfma_f32_16x16x32_bf16 v[32:35], v[182:185], v[216:219], v[32:35]
	v_mfma_f32_16x16x32_bf16 v[24:27], v[158:161], v[224:227], v[24:27]
	v_mfma_f32_16x16x32_bf16 v[16:19], v[182:185], v[224:227], v[16:19]
	v_mfma_f32_16x16x32_bf16 v[8:11], v[158:161], v[232:235], v[8:11]
	v_mfma_f32_16x16x32_bf16 v[0:3], v[182:185], v[232:235], v[0:3]
	v_mfma_f32_16x16x32_bf16 v[48:51], v[158:161], v[190:193], v[64:67]
	v_mfma_f32_16x16x32_bf16 v[52:55], v[186:189], v[212:215], v[52:55]
	v_mfma_f32_16x16x32_bf16 v[40:43], v[178:181], v[220:223], v[40:43]
	v_mfma_f32_16x16x32_bf16 v[32:35], v[186:189], v[220:223], v[32:35]
	v_mfma_f32_16x16x32_bf16 v[24:27], v[178:181], v[228:231], v[24:27]
	v_mfma_f32_16x16x32_bf16 v[16:19], v[186:189], v[228:231], v[16:19]
	v_mfma_f32_16x16x32_bf16 v[8:11], v[178:181], v[236:239], v[8:11]
	v_mfma_f32_16x16x32_bf16 v[0:3], v[186:189], v[236:239], v[0:3]
	v_mfma_f32_16x16x32_bf16 v[48:51], v[178:181], v[212:215], v[48:51]
	s_setprio 0
	s_barrier
	s_add_i32 s80, 0, 0x18000
	s_add_i32 s81, 0, 0x1c000
	v_add_u32_e32 v154, s80, v176
	v_add_u32_e32 v186, s81, v176
	ds_read_b128 v[60:63], v154
	ds_read_b128 v[64:67], v154 offset:1024
	ds_read_b128 v[138:141], v154 offset:2048
	ds_read_b128 v[154:157], v154 offset:3072
	ds_read_b128 v[158:161], v186
	ds_read_b128 v[178:181], v186 offset:1024
	ds_read_b128 v[182:185], v186 offset:2048
	ds_read_b128 v[186:189], v186 offset:3072
	s_add_u32 s76, s90, 0x40000
	s_addc_u32 s77, s91, 0
	s_mov_b32 m0, s17
	v_lshl_add_u64 v[246:247], s[76:77], 0, v[142:143]
	ds_read_b128 v[190:193], v177 offset:32768
	ds_read_b128 v[212:215], v177 offset:33792
	ds_read_b128 v[216:219], v177 offset:34816
	ds_read_b128 v[220:223], v177 offset:35840
	ds_read_b128 v[224:227], v177 offset:36864
	ds_read_b128 v[228:231], v177 offset:37888
	ds_read_b128 v[232:235], v177 offset:38912
	ds_read_b128 v[236:239], v177 offset:39936
	global_load_lds_dwordx4 v[246:247], off
	v_lshl_add_u64 v[246:247], s[76:77], 0, v[146:147]
	s_mov_b32 m0, s18
	s_nop 0
	global_load_lds_dwordx4 v[246:247], off
	s_waitcnt vmcnt(8)
	s_waitcnt lgkmcnt(0)
	s_barrier
	s_setprio 1
	s_waitcnt lgkmcnt(0)
	v_mfma_f32_16x16x32_bf16 v[134:137], v[60:63], v[190:193], v[134:137]
	v_mfma_f32_16x16x32_bf16 v[126:129], v[138:141], v[190:193], v[126:129]
	v_mfma_f32_16x16x32_bf16 v[110:113], v[138:141], v[216:219], v[110:113]
	v_mfma_f32_16x16x32_bf16 v[118:121], v[60:63], v[216:219], v[118:121]
	v_mfma_f32_16x16x32_bf16 v[102:105], v[60:63], v[224:227], v[102:105]
	v_mfma_f32_16x16x32_bf16 v[94:97], v[138:141], v[224:227], v[94:97]
	v_mfma_f32_16x16x32_bf16 v[76:79], v[138:141], v[232:235], v[76:79]
	v_mfma_f32_16x16x32_bf16 v[86:89], v[60:63], v[232:235], v[86:89]
	v_mfma_f32_16x16x32_bf16 v[134:137], v[64:67], v[212:215], v[134:137]
	v_mfma_f32_16x16x32_bf16 v[126:129], v[154:157], v[212:215], v[126:129]
	v_mfma_f32_16x16x32_bf16 v[110:113], v[154:157], v[220:223], v[110:113]
	v_mfma_f32_16x16x32_bf16 v[118:121], v[64:67], v[220:223], v[118:121]
	v_mfma_f32_16x16x32_bf16 v[102:105], v[64:67], v[228:231], v[102:105]
	v_mfma_f32_16x16x32_bf16 v[94:97], v[154:157], v[228:231], v[94:97]
	v_mfma_f32_16x16x32_bf16 v[76:79], v[154:157], v[236:239], v[76:79]
	v_mfma_f32_16x16x32_bf16 v[86:89], v[64:67], v[236:239], v[86:89]
	v_mfma_f32_16x16x32_bf16 v[130:133], v[158:161], v[190:193], v[130:133]
	v_mfma_f32_16x16x32_bf16 v[122:125], v[182:185], v[190:193], v[122:125]
	v_mfma_f32_16x16x32_bf16 v[106:109], v[182:185], v[216:219], v[106:109]
	v_mfma_f32_16x16x32_bf16 v[114:117], v[158:161], v[216:219], v[114:117]
	v_mfma_f32_16x16x32_bf16 v[98:101], v[158:161], v[224:227], v[98:101]
	v_mfma_f32_16x16x32_bf16 v[90:93], v[182:185], v[224:227], v[90:93]
	v_mfma_f32_16x16x32_bf16 v[72:75], v[182:185], v[232:235], v[72:75]
	v_mfma_f32_16x16x32_bf16 v[82:85], v[158:161], v[232:235], v[82:85]
	v_mfma_f32_16x16x32_bf16 v[130:133], v[178:181], v[212:215], v[130:133]
	v_mfma_f32_16x16x32_bf16 v[122:125], v[186:189], v[212:215], v[122:125]
	v_mfma_f32_16x16x32_bf16 v[106:109], v[186:189], v[220:223], v[106:109]
	v_mfma_f32_16x16x32_bf16 v[114:117], v[178:181], v[220:223], v[114:117]
	v_mfma_f32_16x16x32_bf16 v[98:101], v[178:181], v[228:231], v[98:101]
	v_mfma_f32_16x16x32_bf16 v[90:93], v[186:189], v[228:231], v[90:93]
	v_mfma_f32_16x16x32_bf16 v[72:75], v[186:189], v[236:239], v[72:75]
	v_mfma_f32_16x16x32_bf16 v[82:85], v[178:181], v[236:239], v[82:85]
	s_setprio 0
	s_barrier
; #define PG8_STAGE(bufoff, gbase, voff) do { _Pragma("unroll") for (int _i = 0; _i < 2; ++_i) \
;         __builtin_amdgcn_global_load_lds((const unsigned*)((const char*)(gbase) + (voff)[_i]), (PG8_LAS unsigned*)(lds + (bufoff) + ldsw + _i * 8192), 16, 0, 0); } while (0)
; #define PG8_LDA(dst, b, h) do { _Pragma("unroll") for (int m = 0; m < 4; ++m) _Pragma("unroll") for (int k = 0; k < 2; ++k) dst[m][k] = *(const PG8_LAS bf16x8*)(lds + PG8_SA(b, h) + aoff + m * 2048 + k * 1024); } while (0)
; #define PG8_MMA(ai, bj, At, Bt) do { __builtin_amdgcn_s_setprio(1); _Pragma("unroll") for (int m = 0; m < 4; ++m) _Pragma("unroll") for (int n = 0; n < 2; ++n) _Pragma("unroll") for (int k = 0; k < 2; ++k) \
;         acc[ai][bj][m][n] = __builtin_amdgcn_mfma_f32_16x16x32_bf16(Bt[n][k], At[m][k], acc[ai][bj][m][n], 0, 0, 0); __builtin_amdgcn_s_setprio(0); } while (0)
; #define PG8_WAIT_V(n) asm volatile("s_waitcnt vmcnt(" #n ")" ::: "memory")
; #define PG8_WAIT_L(n) asm volatile("s_waitcnt lgkmcnt(" #n ")" ::: "memory")
; #define PG8_BAR __builtin_amdgcn_s_barrier()
; #define PG8_SCHED __builtin_amdgcn_sched_barrier(0)
; template <class Epi, class Sched, bool ALIGN_EPI = false, bool SP2 = false>
; __device__ __forceinline__ void gemm_phase(PG8_LAS unsigned char* lds, const Gemm g, const Sched& S, const Epi& E) {
;     ...
;         for (int t = 0; t < nt; t += 2) {
;     ...
;             PG8_LDA(At, 1, 1); PG8_STAGE(PG8_SB(1, 0), b3, voffB); PG8_STAGE(PG8_SB(1, 1), b3 + hstep, voffB); PG8_STAGE(PG8_SA(1, 0), a3, voffA);
;             PG8_WAIT_V(8); PG8_WAIT_L(0); PG8_BAR; PG8_MMA(1, 0, At, B0); PG8_MMA(1, 1, At, B1); PG8_BAR; PG8_SCHED;
;     ...
;         if constexpr (ALIGN_EPI) { if (wr == 0) PG8_BAR; }
	s_add_i32 s76, s80, s13
	v_lshl_add_u64 v[194:195], v[194:195], 0, s[0:1]
	s_mov_b32 m0, s76
	ds_read_b128 v[190:193], v177 offset:49152
	ds_read_b128 v[212:215], v177 offset:50176
	ds_read_b128 v[216:219], v177 offset:51200
	ds_read_b128 v[220:223], v177 offset:52224
	ds_read_b128 v[224:227], v177 offset:53248
	ds_read_b128 v[228:231], v177 offset:54272
	ds_read_b128 v[232:235], v177 offset:55296
	ds_read_b128 v[236:239], v177 offset:56320
	global_load_lds_dwordx4 v[194:195], off
	s_add_i32 m0, s76, 0x2000
	s_add_u32 s76, s88, 0x40080
	v_lshl_add_u64 v[194:195], v[240:241], 0, s[0:1]
	s_addc_u32 s77, s89, 0
	s_add_i32 s80, s81, s13
	global_load_lds_dwordx4 v[194:195], off
	v_lshl_add_u64 v[194:195], s[76:77], 0, v[144:145]
	s_mov_b32 m0, s80
	s_nop 0
	global_load_lds_dwordx4 v[194:195], off
	v_lshl_add_u64 v[194:195], s[76:77], 0, v[148:149]
	s_add_i32 m0, s80, 0x2000
	s_nop 0
	global_load_lds_dwordx4 v[194:195], off
	v_lshl_add_u64 v[194:195], v[242:243], 0, s[0:1]
	s_mov_b32 m0, s21
	s_nop 0
	global_load_lds_dwordx4 v[194:195], off
	v_lshl_add_u64 v[194:195], v[244:245], 0, s[0:1]
	s_mov_b32 m0, s33
	s_nop 0
	global_load_lds_dwordx4 v[194:195], off
	s_waitcnt vmcnt(8)
	s_waitcnt lgkmcnt(0)
	s_barrier
	s_setprio 1
	s_waitcnt lgkmcnt(0)
	v_mfma_f32_16x16x32_bf16 v[68:71], v[60:63], v[190:193], v[68:71]
	v_mfma_f32_16x16x32_bf16 v[56:59], v[138:141], v[190:193], v[56:59]
	v_mfma_f32_16x16x32_bf16 v[36:39], v[138:141], v[216:219], v[36:39]
	v_mfma_f32_16x16x32_bf16 v[44:47], v[60:63], v[216:219], v[44:47]
	v_mfma_f32_16x16x32_bf16 v[28:31], v[60:63], v[224:227], v[28:31]
	v_mfma_f32_16x16x32_bf16 v[20:23], v[138:141], v[224:227], v[20:23]
	v_mfma_f32_16x16x32_bf16 v[4:7], v[138:141], v[232:235], v[4:7]
	v_mfma_f32_16x16x32_bf16 v[12:15], v[60:63], v[232:235], v[12:15]
	v_mfma_f32_16x16x32_bf16 v[68:71], v[64:67], v[212:215], v[68:71]
	v_mfma_f32_16x16x32_bf16 v[56:59], v[154:157], v[212:215], v[56:59]
	v_mfma_f32_16x16x32_bf16 v[36:39], v[154:157], v[220:223], v[36:39]
	v_mfma_f32_16x16x32_bf16 v[44:47], v[64:67], v[220:223], v[44:47]
	v_mfma_f32_16x16x32_bf16 v[28:31], v[64:67], v[228:231], v[28:31]
	v_mfma_f32_16x16x32_bf16 v[20:23], v[154:157], v[228:231], v[20:23]
	v_mfma_f32_16x16x32_bf16 v[4:7], v[154:157], v[236:239], v[4:7]
	v_mfma_f32_16x16x32_bf16 v[12:15], v[64:67], v[236:239], v[12:15]
	v_mfma_f32_16x16x32_bf16 v[48:51], v[158:161], v[190:193], v[48:51]
	v_mfma_f32_16x16x32_bf16 v[64:67], v[178:181], v[212:215], v[48:51]
	v_mfma_f32_16x16x32_bf16 v[48:51], v[182:185], v[190:193], v[52:55]
	v_mfma_f32_16x16x32_bf16 v[40:43], v[158:161], v[216:219], v[40:43]
	v_mfma_f32_16x16x32_bf16 v[32:35], v[182:185], v[216:219], v[32:35]
	v_mfma_f32_16x16x32_bf16 v[24:27], v[158:161], v[224:227], v[24:27]
	v_mfma_f32_16x16x32_bf16 v[16:19], v[182:185], v[224:227], v[16:19]
	v_mfma_f32_16x16x32_bf16 v[8:11], v[158:161], v[232:235], v[8:11]
	v_mfma_f32_16x16x32_bf16 v[0:3], v[182:185], v[232:235], v[0:3]
	v_mfma_f32_16x16x32_bf16 v[52:55], v[186:189], v[212:215], v[48:51]
	v_mfma_f32_16x16x32_bf16 v[40:43], v[178:181], v[220:223], v[40:43]
	v_mfma_f32_16x16x32_bf16 v[32:35], v[186:189], v[220:223], v[32:35]
	v_mfma_f32_16x16x32_bf16 v[24:27], v[178:181], v[228:231], v[24:27]
	v_mfma_f32_16x16x32_bf16 v[16:19], v[186:189], v[228:231], v[16:19]
	v_mfma_f32_16x16x32_bf16 v[0:3], v[186:189], v[236:239], v[0:3]
	v_mfma_f32_16x16x32_bf16 v[8:11], v[178:181], v[236:239], v[8:11]
	s_setprio 0
	s_barrier
	s_add_i32 s75, s75, 2
	s_add_u32 s86, s86, 0x100
	s_addc_u32 s87, s87, 0
	s_add_u32 s69, s69, 0x100
	s_addc_u32 s71, s71, 0
	s_cmp_gt_u32 s75, 13
	s_cbranch_scc0 .LBB0_236
	s_and_b64 vcc, exec, s[30:31]
	s_cbranch_vccz .LBB0_239
	s_barrier

; #define PG8_STAGE(bufoff, gbase, voff) do { _Pragma("unroll") for (int _i = 0; _i < 2; ++_i) \
;         __builtin_amdgcn_global_load_lds((const unsigned*)((const char*)(gbase) + (voff)[_i]), (PG8_LAS unsigned*)(lds + (bufoff) + ldsw + _i * 8192), 16, 0, 0); } while (0)
; #define PG8_LDA(dst, b, h) do { _Pragma("unroll") for (int m = 0; m < 4; ++m) _Pragma("unroll") for (int k = 0; k < 2; ++k) dst[m][k] = *(const PG8_LAS bf16x8*)(lds + PG8_SA(b, h) + aoff + m * 2048 + k * 1024); } while (0)
; #define PG8_LDB(dst, b, h) do { _Pragma("unroll") for (int n = 0; n < 2; ++n) _Pragma("unroll") for (int k = 0; k < 2; ++k) dst[n][k] = *(const PG8_LAS bf16x8*)(lds + PG8_SB(b, h) + boff + n * 2048 + k * 1024); } while (0)
; #define PG8_MMA(ai, bj, At, Bt) do { __builtin_amdgcn_s_setprio(1); _Pragma("unroll") for (int m = 0; m < 4; ++m) _Pragma("unroll") for (int n = 0; n < 2; ++n) _Pragma("unroll") for (int k = 0; k < 2; ++k) \
;         acc[ai][bj][m][n] = __builtin_amdgcn_mfma_f32_16x16x32_bf16(Bt[n][k], At[m][k], acc[ai][bj][m][n], 0, 0, 0); __builtin_amdgcn_s_setprio(0); } while (0)
; #define PG8_WAIT_V(n) asm volatile("s_waitcnt vmcnt(" #n ")" ::: "memory")
; #define PG8_WAIT_L(n) asm volatile("s_waitcnt lgkmcnt(" #n ")" ::: "memory")
; template <class Epi, class Sched, bool ALIGN_EPI = false, bool SP2 = false>
; __device__ __forceinline__ void gemm_phase(PG8_LAS unsigned char* lds, const Gemm g, const Sched& S, const Epi& E) {
;     ...
;             const bool last = (t == nt - 2);
;             const char* a1 = cA + (size_t)(t + 1) * kstep;
;             const char* a2 = last ? nA : cA + (size_t)(t + 2) * kstep; const char* b2 = last ? nB : cB + (size_t)(t + 2) * kstep;
;             const char* a3 = a2 + kstep; const char* b3 = b2 + kstep;
;             if (last && has_next) S.a_ready(nxt);
;             if constexpr (SP2) {
;             PG8_LDB(B0, 0, 0); PG8_LDB(B1, 0, 1); PG8_SCHED; PG8_LDA(At, 0, 0); PG8_STAGE(PG8_SA(1, 1), a1 + hstep, voffA);
;             PG8_WAIT_V(8); PG8_WAIT_L(0); PG8_BAR; PG8_MMA(0, 0, At, B0); PG8_MMA(0, 1, At, B1); PG8_BAR; PG8_SCHED;
;             PG8_LDA(At, 0, 1); PG8_STAGE(PG8_SB(0, 0), b2, voffB); PG8_STAGE(PG8_SB(0, 1), b2 + hstep, voffB); PG8_STAGE(PG8_SA(0, 0), a2, voffA);
;             PG8_WAIT_V(8); PG8_WAIT_L(0); PG8_BAR; PG8_MMA(1, 0, At, B0); PG8_MMA(1, 1, At, B1); PG8_BAR; PG8_SCHED;
.LBB0_316:
	s_add_u32 s14, s40, 0xfffc0080
	s_addc_u32 s15, s41, -1
	s_add_i32 s16, 0, 0x10000
	s_cmp_eq_u32 s13, 12
	s_cselect_b32 s71, s3, s15
	s_cselect_b32 s70, s8, s14
	s_cselect_b32 s43, s9, s12
	s_cselect_b32 s42, s10, s11
	s_add_i32 s17, 0, 0x14000
	s_waitcnt lgkmcnt(0)
	v_add_u32_e32 v44, s16, v214
	v_add_u32_e32 v102, s17, v214
	ds_read_b128 v[32:35], v44
	ds_read_b128 v[36:39], v44 offset:1024
	ds_read_b128 v[40:43], v44 offset:2048
	ds_read_b128 v[44:47], v44 offset:3072
	ds_read_b128 v[90:93], v102
	ds_read_b128 v[94:97], v102 offset:1024
	ds_read_b128 v[98:101], v102 offset:2048
	ds_read_b128 v[102:105], v102 offset:3072
	v_lshl_add_u64 v[194:195], s[40:41], 0, v[178:179]
	s_add_i32 m0, s97, 0xc000
	ds_read_b128 v[182:185], v215
	ds_read_b128 v[186:189], v215 offset:1024
	ds_read_b128 v[190:193], v215 offset:2048
	ds_read_b128 v[216:219], v215 offset:3072
	ds_read_b128 v[220:223], v215 offset:4096
	ds_read_b128 v[224:227], v215 offset:5120
	ds_read_b128 v[228:231], v215 offset:6144
	ds_read_b128 v[232:235], v215 offset:7168
	global_load_lds_dwordx4 v[194:195], off
	v_lshl_add_u64 v[194:195], s[40:41], 0, v[180:181]
	s_add_i32 m0, s97, 0xe000
	s_nop 0
	global_load_lds_dwordx4 v[194:195], off
	s_waitcnt vmcnt(8)
	s_waitcnt lgkmcnt(0)
	s_barrier
	s_setprio 1
	s_waitcnt lgkmcnt(0)
	v_mfma_f32_16x16x32_bf16 v[158:161], v[32:35], v[182:185], v[158:161]
	v_mfma_f32_16x16x32_bf16 v[154:157], v[40:43], v[182:185], v[154:157]
	v_mfma_f32_16x16x32_bf16 v[138:141], v[40:43], v[190:193], v[138:141]
	v_mfma_f32_16x16x32_bf16 v[142:145], v[32:35], v[190:193], v[142:145]
	v_mfma_f32_16x16x32_bf16 v[126:129], v[32:35], v[220:223], v[126:129]
	v_mfma_f32_16x16x32_bf16 v[122:125], v[40:43], v[220:223], v[122:125]
	v_mfma_f32_16x16x32_bf16 v[106:109], v[40:43], v[228:231], v[106:109]
	v_mfma_f32_16x16x32_bf16 v[110:113], v[32:35], v[228:231], v[110:113]
	v_mfma_f32_16x16x32_bf16 v[158:161], v[36:39], v[186:189], v[158:161]
	v_mfma_f32_16x16x32_bf16 v[154:157], v[44:47], v[186:189], v[154:157]
	v_mfma_f32_16x16x32_bf16 v[138:141], v[44:47], v[216:219], v[138:141]
	v_mfma_f32_16x16x32_bf16 v[142:145], v[36:39], v[216:219], v[142:145]
	v_mfma_f32_16x16x32_bf16 v[126:129], v[36:39], v[224:227], v[126:129]
	v_mfma_f32_16x16x32_bf16 v[122:125], v[44:47], v[224:227], v[122:125]
	v_mfma_f32_16x16x32_bf16 v[106:109], v[44:47], v[232:235], v[106:109]
	v_mfma_f32_16x16x32_bf16 v[110:113], v[36:39], v[232:235], v[110:113]
	v_mfma_f32_16x16x32_bf16 v[150:153], v[90:93], v[182:185], v[150:153]
	v_mfma_f32_16x16x32_bf16 v[146:149], v[98:101], v[182:185], v[146:149]
	v_mfma_f32_16x16x32_bf16 v[130:133], v[98:101], v[190:193], v[130:133]
	v_mfma_f32_16x16x32_bf16 v[134:137], v[90:93], v[190:193], v[134:137]
	v_mfma_f32_16x16x32_bf16 v[118:121], v[90:93], v[220:223], v[118:121]
	v_mfma_f32_16x16x32_bf16 v[114:117], v[98:101], v[220:223], v[114:117]
	v_mfma_f32_16x16x32_bf16 v[82:85], v[98:101], v[228:231], v[82:85]
	v_mfma_f32_16x16x32_bf16 v[86:89], v[90:93], v[228:231], v[86:89]
	v_mfma_f32_16x16x32_bf16 v[150:153], v[94:97], v[186:189], v[150:153]
	v_mfma_f32_16x16x32_bf16 v[146:149], v[102:105], v[186:189], v[146:149]
	v_mfma_f32_16x16x32_bf16 v[130:133], v[102:105], v[216:219], v[130:133]
	v_mfma_f32_16x16x32_bf16 v[134:137], v[94:97], v[216:219], v[134:137]
	v_mfma_f32_16x16x32_bf16 v[118:121], v[94:97], v[224:227], v[118:121]
	v_mfma_f32_16x16x32_bf16 v[114:117], v[102:105], v[224:227], v[114:117]
	v_mfma_f32_16x16x32_bf16 v[82:85], v[102:105], v[232:235], v[82:85]
	v_mfma_f32_16x16x32_bf16 v[86:89], v[94:97], v[232:235], v[86:89]
	s_setprio 0
	s_barrier
	s_add_i32 s14, s16, s95
	v_lshl_add_u64 v[194:195], s[42:43], 0, v[174:175]
	s_mov_b32 m0, s14
	ds_read_b128 v[182:185], v215 offset:16384
	ds_read_b128 v[186:189], v215 offset:17408
	ds_read_b128 v[190:193], v215 offset:18432
	ds_read_b128 v[216:219], v215 offset:19456
	ds_read_b128 v[220:223], v215 offset:20480
	ds_read_b128 v[224:227], v215 offset:21504
	ds_read_b128 v[228:231], v215 offset:22528
	ds_read_b128 v[232:235], v215 offset:23552
	global_load_lds_dwordx4 v[194:195], off
	s_add_i32 m0, s14, 0x2000
	s_add_u32 s14, s42, 0x40000
	v_lshl_add_u64 v[236:237], s[42:43], 0, v[176:177]
	s_addc_u32 s15, s43, 0
	s_add_i32 s16, s17, s95
	global_load_lds_dwordx4 v[236:237], off
	v_lshl_add_u64 v[238:239], s[14:15], 0, v[174:175]
	s_mov_b32 m0, s16
	v_lshl_add_u64 v[240:241], s[70:71], 0, v[176:177]
	global_load_lds_dwordx4 v[238:239], off
	v_lshl_add_u64 v[238:239], s[14:15], 0, v[176:177]
	s_add_i32 m0, s16, 0x2000
	s_nop 0
	global_load_lds_dwordx4 v[238:239], off
	v_lshl_add_u64 v[238:239], s[70:71], 0, v[174:175]
	s_mov_b32 m0, s97
	s_nop 0
	global_load_lds_dwordx4 v[238:239], off
	s_mov_b32 m0, s98
	s_nop 0
	global_load_lds_dwordx4 v[240:241], off
	s_waitcnt vmcnt(8)
	s_waitcnt lgkmcnt(0)
	s_barrier
; #define PG8_STAGE(bufoff, gbase, voff) do { _Pragma("unroll") for (int _i = 0; _i < 2; ++_i) \
;         __builtin_amdgcn_global_load_lds((const unsigned*)((const char*)(gbase) + (voff)[_i]), (PG8_LAS unsigned*)(lds + (bufoff) + ldsw + _i * 8192), 16, 0, 0); } while (0)
; #define PG8_LDA(dst, b, h) do { _Pragma("unroll") for (int m = 0; m < 4; ++m) _Pragma("unroll") for (int k = 0; k < 2; ++k) dst[m][k] = *(const PG8_LAS bf16x8*)(lds + PG8_SA(b, h) + aoff + m * 2048 + k * 1024); } while (0)
; #define PG8_LDB(dst, b, h) do { _Pragma("unroll") for (int n = 0; n < 2; ++n) _Pragma("unroll") for (int k = 0; k < 2; ++k) dst[n][k] = *(const PG8_LAS bf16x8*)(lds + PG8_SB(b, h) + boff + n * 2048 + k * 1024); } while (0)
; #define PG8_MMA(ai, bj, At, Bt) do { __builtin_amdgcn_s_setprio(1); _Pragma("unroll") for (int m = 0; m < 4; ++m) _Pragma("unroll") for (int n = 0; n < 2; ++n) _Pragma("unroll") for (int k = 0; k < 2; ++k) \
;         acc[ai][bj][m][n] = __builtin_amdgcn_mfma_f32_16x16x32_bf16(Bt[n][k], At[m][k], acc[ai][bj][m][n], 0, 0, 0); __builtin_amdgcn_s_setprio(0); } while (0)
; #define PG8_WAIT_V(n) asm volatile("s_waitcnt vmcnt(" #n ")" ::: "memory")
; #define PG8_WAIT_L(n) asm volatile("s_waitcnt lgkmcnt(" #n ")" ::: "memory")
; #define PG8_BAR __builtin_amdgcn_s_barrier()
; #define PG8_SCHED __builtin_amdgcn_sched_barrier(0)
; template <class Epi, class Sched, bool ALIGN_EPI = false, bool SP2 = false>
; __device__ __forceinline__ void gemm_phase(PG8_LAS unsigned char* lds, const Gemm g, const Sched& S, const Epi& E) {
;     ...
;             PG8_WAIT_V(8); PG8_WAIT_L(0); PG8_BAR; PG8_MMA(1, 0, At, B0); PG8_MMA(1, 1, At, B1); PG8_BAR; PG8_SCHED;
;             PG8_LDB(B0, 1, 0); PG8_LDB(B1, 1, 1); PG8_SCHED; PG8_LDA(At, 1, 0); PG8_STAGE(PG8_SA(0, 1), a2 + hstep, voffA);
;             PG8_WAIT_V(8); PG8_WAIT_L(0); PG8_BAR; PG8_MMA(0, 0, At, B0); PG8_MMA(0, 1, At, B1); PG8_BAR; PG8_SCHED;
	s_setprio 1
	s_waitcnt lgkmcnt(0)
	v_mfma_f32_16x16x32_bf16 v[76:79], v[32:35], v[182:185], v[76:79]
	v_mfma_f32_16x16x32_bf16 v[72:75], v[40:43], v[182:185], v[72:75]
	v_mfma_f32_16x16x32_bf16 v[56:59], v[40:43], v[190:193], v[56:59]
	v_mfma_f32_16x16x32_bf16 v[60:63], v[32:35], v[190:193], v[60:63]
	v_mfma_f32_16x16x32_bf16 v[28:31], v[32:35], v[220:223], v[28:31]
	v_mfma_f32_16x16x32_bf16 v[24:27], v[40:43], v[220:223], v[24:27]
	v_mfma_f32_16x16x32_bf16 v[8:11], v[40:43], v[228:231], v[8:11]
	v_mfma_f32_16x16x32_bf16 v[12:15], v[32:35], v[228:231], v[12:15]
	v_mfma_f32_16x16x32_bf16 v[76:79], v[36:39], v[186:189], v[76:79]
	v_mfma_f32_16x16x32_bf16 v[72:75], v[44:47], v[186:189], v[72:75]
	v_mfma_f32_16x16x32_bf16 v[56:59], v[44:47], v[216:219], v[56:59]
	v_mfma_f32_16x16x32_bf16 v[60:63], v[36:39], v[216:219], v[60:63]
	v_mfma_f32_16x16x32_bf16 v[28:31], v[36:39], v[224:227], v[28:31]
	v_mfma_f32_16x16x32_bf16 v[24:27], v[44:47], v[224:227], v[24:27]
	v_mfma_f32_16x16x32_bf16 v[8:11], v[44:47], v[232:235], v[8:11]
	v_mfma_f32_16x16x32_bf16 v[12:15], v[36:39], v[232:235], v[12:15]
	v_mfma_f32_16x16x32_bf16 v[20:23], v[90:93], v[220:223], v[20:23]
	v_mfma_f32_16x16x32_bf16 v[16:19], v[98:101], v[220:223], v[16:19]
	v_mfma_f32_16x16x32_bf16 v[0:3], v[98:101], v[228:231], v[0:3]
	v_mfma_f32_16x16x32_bf16 v[4:7], v[90:93], v[228:231], v[4:7]
	v_mfma_f32_16x16x32_bf16 v[32:35], v[90:93], v[182:185], v[68:71]
	v_mfma_f32_16x16x32_bf16 v[36:39], v[98:101], v[182:185], v[64:67]
	v_mfma_f32_16x16x32_bf16 v[44:47], v[98:101], v[190:193], v[48:51]
	v_mfma_f32_16x16x32_bf16 v[40:43], v[90:93], v[190:193], v[52:55]
	v_mfma_f32_16x16x32_bf16 v[20:23], v[94:97], v[224:227], v[20:23]
	v_mfma_f32_16x16x32_bf16 v[16:19], v[102:105], v[224:227], v[16:19]
	v_mfma_f32_16x16x32_bf16 v[0:3], v[102:105], v[232:235], v[0:3]
	v_mfma_f32_16x16x32_bf16 v[4:7], v[94:97], v[232:235], v[4:7]
	v_mfma_f32_16x16x32_bf16 v[32:35], v[94:97], v[186:189], v[32:35]
	v_mfma_f32_16x16x32_bf16 v[36:39], v[102:105], v[186:189], v[36:39]
	v_mfma_f32_16x16x32_bf16 v[44:47], v[102:105], v[216:219], v[44:47]
	v_mfma_f32_16x16x32_bf16 v[40:43], v[94:97], v[216:219], v[40:43]
	s_setprio 0
	s_barrier
	s_add_i32 s16, 0, 0x18000
	s_add_i32 s17, 0, 0x1c000
	v_add_u32_e32 v68, s16, v214
	v_add_u32_e32 v102, s17, v214
	ds_read_b128 v[48:51], v68
	ds_read_b128 v[52:55], v68 offset:1024
	ds_read_b128 v[64:67], v68 offset:2048
	ds_read_b128 v[68:71], v68 offset:3072
	ds_read_b128 v[90:93], v102
	ds_read_b128 v[94:97], v102 offset:1024
	ds_read_b128 v[98:101], v102 offset:2048
	ds_read_b128 v[102:105], v102 offset:3072
	s_add_u32 s14, s70, 0x40000
	s_addc_u32 s15, s71, 0
	s_mov_b32 m0, s99
	v_lshl_add_u64 v[242:243], s[14:15], 0, v[174:175]
	ds_read_b128 v[182:185], v215 offset:32768
	ds_read_b128 v[186:189], v215 offset:33792
	ds_read_b128 v[190:193], v215 offset:34816
	ds_read_b128 v[216:219], v215 offset:35840
	ds_read_b128 v[220:223], v215 offset:36864
	ds_read_b128 v[224:227], v215 offset:37888
	ds_read_b128 v[228:231], v215 offset:38912
	ds_read_b128 v[232:235], v215 offset:39936
	global_load_lds_dwordx4 v[242:243], off
	v_lshl_add_u64 v[242:243], s[14:15], 0, v[176:177]
	s_mov_b32 m0, s94
	s_nop 0
	global_load_lds_dwordx4 v[242:243], off
	s_waitcnt vmcnt(8)
	s_waitcnt lgkmcnt(0)
	s_barrier
	s_setprio 1
	s_waitcnt lgkmcnt(0)
	v_mfma_f32_16x16x32_bf16 v[158:161], v[48:51], v[182:185], v[158:161]
	v_mfma_f32_16x16x32_bf16 v[154:157], v[64:67], v[182:185], v[154:157]
	v_mfma_f32_16x16x32_bf16 v[138:141], v[64:67], v[190:193], v[138:141]
	v_mfma_f32_16x16x32_bf16 v[142:145], v[48:51], v[190:193], v[142:145]
	v_mfma_f32_16x16x32_bf16 v[126:129], v[48:51], v[220:223], v[126:129]
	v_mfma_f32_16x16x32_bf16 v[122:125], v[64:67], v[220:223], v[122:125]
	v_mfma_f32_16x16x32_bf16 v[106:109], v[64:67], v[228:231], v[106:109]
	v_mfma_f32_16x16x32_bf16 v[110:113], v[48:51], v[228:231], v[110:113]
	v_mfma_f32_16x16x32_bf16 v[158:161], v[52:55], v[186:189], v[158:161]
	v_mfma_f32_16x16x32_bf16 v[154:157], v[68:71], v[186:189], v[154:157]
	v_mfma_f32_16x16x32_bf16 v[138:141], v[68:71], v[216:219], v[138:141]
	v_mfma_f32_16x16x32_bf16 v[142:145], v[52:55], v[216:219], v[142:145]
	v_mfma_f32_16x16x32_bf16 v[126:129], v[52:55], v[224:227], v[126:129]
	v_mfma_f32_16x16x32_bf16 v[122:125], v[68:71], v[224:227], v[122:125]
	v_mfma_f32_16x16x32_bf16 v[106:109], v[68:71], v[232:235], v[106:109]
	v_mfma_f32_16x16x32_bf16 v[110:113], v[52:55], v[232:235], v[110:113]
	v_mfma_f32_16x16x32_bf16 v[150:153], v[90:93], v[182:185], v[150:153]
	v_mfma_f32_16x16x32_bf16 v[146:149], v[98:101], v[182:185], v[146:149]
	v_mfma_f32_16x16x32_bf16 v[130:133], v[98:101], v[190:193], v[130:133]
	v_mfma_f32_16x16x32_bf16 v[134:137], v[90:93], v[190:193], v[134:137]
	v_mfma_f32_16x16x32_bf16 v[118:121], v[90:93], v[220:223], v[118:121]
	v_mfma_f32_16x16x32_bf16 v[114:117], v[98:101], v[220:223], v[114:117]
	v_mfma_f32_16x16x32_bf16 v[82:85], v[98:101], v[228:231], v[82:85]
	v_mfma_f32_16x16x32_bf16 v[86:89], v[90:93], v[228:231], v[86:89]
	v_mfma_f32_16x16x32_bf16 v[150:153], v[94:97], v[186:189], v[150:153]
	v_mfma_f32_16x16x32_bf16 v[146:149], v[102:105], v[186:189], v[146:149]
	v_mfma_f32_16x16x32_bf16 v[130:133], v[102:105], v[216:219], v[130:133]
	v_mfma_f32_16x16x32_bf16 v[134:137], v[94:97], v[216:219], v[134:137]
	v_mfma_f32_16x16x32_bf16 v[118:121], v[94:97], v[224:227], v[118:121]
	v_mfma_f32_16x16x32_bf16 v[114:117], v[102:105], v[224:227], v[114:117]
	v_mfma_f32_16x16x32_bf16 v[82:85], v[102:105], v[232:235], v[82:85]
	v_mfma_f32_16x16x32_bf16 v[86:89], v[94:97], v[232:235], v[86:89]
	s_setprio 0
	s_barrier
; #define PG8_STAGE(bufoff, gbase, voff) do { _Pragma("unroll") for (int _i = 0; _i < 2; ++_i) \
;         __builtin_amdgcn_global_load_lds((const unsigned*)((const char*)(gbase) + (voff)[_i]), (PG8_LAS unsigned*)(lds + (bufoff) + ldsw + _i * 8192), 16, 0, 0); } while (0)
; #define PG8_LDA(dst, b, h) do { _Pragma("unroll") for (int m = 0; m < 4; ++m) _Pragma("unroll") for (int k = 0; k < 2; ++k) dst[m][k] = *(const PG8_LAS bf16x8*)(lds + PG8_SA(b, h) + aoff + m * 2048 + k * 1024); } while (0)
; #define PG8_MMA(ai, bj, At, Bt) do { __builtin_amdgcn_s_setprio(1); _Pragma("unroll") for (int m = 0; m < 4; ++m) _Pragma("unroll") for (int n = 0; n < 2; ++n) _Pragma("unroll") for (int k = 0; k < 2; ++k) \
;         acc[ai][bj][m][n] = __builtin_amdgcn_mfma_f32_16x16x32_bf16(Bt[n][k], At[m][k], acc[ai][bj][m][n], 0, 0, 0); __builtin_amdgcn_s_setprio(0); } while (0)
; #define PG8_WAIT_V(n) asm volatile("s_waitcnt vmcnt(" #n ")" ::: "memory")
; #define PG8_WAIT_L(n) asm volatile("s_waitcnt lgkmcnt(" #n ")" ::: "memory")
; #define PG8_BAR __builtin_amdgcn_s_barrier()
; #define PG8_SCHED __builtin_amdgcn_sched_barrier(0)
; template <class Epi, class Sched, bool ALIGN_EPI = false, bool SP2 = false>
; __device__ __forceinline__ void gemm_phase(PG8_LAS unsigned char* lds, const Gemm g, const Sched& S, const Epi& E) {
;     ...
;         for (int t = 0; t < nt; t += 2) {
;     ...
;             PG8_LDA(At, 1, 1); PG8_STAGE(PG8_SB(1, 0), b3, voffB); PG8_STAGE(PG8_SB(1, 1), b3 + hstep, voffB); PG8_STAGE(PG8_SA(1, 0), a3, voffA);
;             PG8_WAIT_V(8); PG8_WAIT_L(0); PG8_BAR; PG8_MMA(1, 0, At, B0); PG8_MMA(1, 1, At, B1); PG8_BAR; PG8_SCHED;
;     ...
;         if constexpr (ALIGN_EPI) { if (wr == 0) PG8_BAR; }
	s_add_i32 s14, s16, s95
	v_lshl_add_u64 v[194:195], v[194:195], 0, s[0:1]
	s_mov_b32 m0, s14
	ds_read_b128 v[182:185], v215 offset:49152
	ds_read_b128 v[186:189], v215 offset:50176
	ds_read_b128 v[190:193], v215 offset:51200
	ds_read_b128 v[216:219], v215 offset:52224
	ds_read_b128 v[220:223], v215 offset:53248
	ds_read_b128 v[224:227], v215 offset:54272
	ds_read_b128 v[228:231], v215 offset:55296
	ds_read_b128 v[232:235], v215 offset:56320
	global_load_lds_dwordx4 v[194:195], off
	s_add_i32 m0, s14, 0x2000
	s_add_u32 s14, s42, 0x40080
	v_lshl_add_u64 v[194:195], v[236:237], 0, s[0:1]
	s_addc_u32 s15, s43, 0
	s_add_i32 s16, s17, s95
	global_load_lds_dwordx4 v[194:195], off
	v_lshl_add_u64 v[194:195], s[14:15], 0, v[174:175]
	s_mov_b32 m0, s16
	s_nop 0
	global_load_lds_dwordx4 v[194:195], off
	v_lshl_add_u64 v[194:195], s[14:15], 0, v[176:177]
	s_add_i32 m0, s16, 0x2000
	s_nop 0
	global_load_lds_dwordx4 v[194:195], off
	v_lshl_add_u64 v[194:195], v[238:239], 0, s[0:1]
	s_mov_b32 m0, s44
	s_nop 0
	global_load_lds_dwordx4 v[194:195], off
	v_lshl_add_u64 v[194:195], v[240:241], 0, s[0:1]
	s_mov_b32 m0, s45
	s_nop 0
	global_load_lds_dwordx4 v[194:195], off
	s_waitcnt vmcnt(8)
	s_waitcnt lgkmcnt(0)
	s_barrier
	s_setprio 1
	s_waitcnt lgkmcnt(0)
	v_mfma_f32_16x16x32_bf16 v[76:79], v[48:51], v[182:185], v[76:79]
	v_mfma_f32_16x16x32_bf16 v[72:75], v[64:67], v[182:185], v[72:75]
	v_mfma_f32_16x16x32_bf16 v[56:59], v[64:67], v[190:193], v[56:59]
	v_mfma_f32_16x16x32_bf16 v[60:63], v[48:51], v[190:193], v[60:63]
	v_mfma_f32_16x16x32_bf16 v[28:31], v[48:51], v[220:223], v[28:31]
	v_mfma_f32_16x16x32_bf16 v[24:27], v[64:67], v[220:223], v[24:27]
	v_mfma_f32_16x16x32_bf16 v[8:11], v[64:67], v[228:231], v[8:11]
	v_mfma_f32_16x16x32_bf16 v[12:15], v[48:51], v[228:231], v[12:15]
	v_mfma_f32_16x16x32_bf16 v[76:79], v[52:55], v[186:189], v[76:79]
	v_mfma_f32_16x16x32_bf16 v[72:75], v[68:71], v[186:189], v[72:75]
	v_mfma_f32_16x16x32_bf16 v[56:59], v[68:71], v[216:219], v[56:59]
	v_mfma_f32_16x16x32_bf16 v[60:63], v[52:55], v[216:219], v[60:63]
	v_mfma_f32_16x16x32_bf16 v[28:31], v[52:55], v[224:227], v[28:31]
	v_mfma_f32_16x16x32_bf16 v[24:27], v[68:71], v[224:227], v[24:27]
	v_mfma_f32_16x16x32_bf16 v[8:11], v[68:71], v[232:235], v[8:11]
	v_mfma_f32_16x16x32_bf16 v[12:15], v[52:55], v[232:235], v[12:15]
	v_mfma_f32_16x16x32_bf16 v[32:35], v[90:93], v[182:185], v[32:35]
	v_mfma_f32_16x16x32_bf16 v[68:71], v[94:97], v[186:189], v[32:35]
	v_mfma_f32_16x16x32_bf16 v[32:35], v[98:101], v[182:185], v[36:39]
	v_mfma_f32_16x16x32_bf16 v[64:67], v[102:105], v[186:189], v[32:35]
	v_mfma_f32_16x16x32_bf16 v[32:35], v[90:93], v[190:193], v[40:43]
	v_mfma_f32_16x16x32_bf16 v[52:55], v[94:97], v[216:219], v[32:35]
	v_mfma_f32_16x16x32_bf16 v[32:35], v[98:101], v[190:193], v[44:47]
	v_mfma_f32_16x16x32_bf16 v[20:23], v[90:93], v[220:223], v[20:23]
	v_mfma_f32_16x16x32_bf16 v[16:19], v[98:101], v[220:223], v[16:19]
	v_mfma_f32_16x16x32_bf16 v[4:7], v[90:93], v[228:231], v[4:7]
	v_mfma_f32_16x16x32_bf16 v[0:3], v[98:101], v[228:231], v[0:3]
	v_mfma_f32_16x16x32_bf16 v[48:51], v[102:105], v[216:219], v[32:35]
	v_mfma_f32_16x16x32_bf16 v[20:23], v[94:97], v[224:227], v[20:23]
	v_mfma_f32_16x16x32_bf16 v[16:19], v[102:105], v[224:227], v[16:19]
	v_mfma_f32_16x16x32_bf16 v[0:3], v[102:105], v[232:235], v[0:3]
	v_mfma_f32_16x16x32_bf16 v[4:7], v[94:97], v[232:235], v[4:7]
	s_setprio 0
	s_barrier
	s_add_i32 s13, s13, 2
	s_add_u32 s40, s40, 0x100
	s_addc_u32 s41, s41, 0
	s_add_u32 s11, s11, 0x100
	s_addc_u32 s12, s12, 0
	s_cmp_gt_u32 s13, 13
	s_cbranch_scc0 .LBB0_316
	s_and_b64 vcc, exec, s[22:23]
	s_cbranch_vccz .LBB0_319
	s_barrier

; #define PG8_STAGE(bufoff, gbase, voff) do { _Pragma("unroll") for (int _i = 0; _i < 2; ++_i) \
;         __builtin_amdgcn_global_load_lds((const unsigned*)((const char*)(gbase) + (voff)[_i]), (PG8_LAS unsigned*)(lds + (bufoff) + ldsw + _i * 8192), 16, 0, 0); } while (0)
; #define PG8_LDA(dst, b, h) do { _Pragma("unroll") for (int m = 0; m < 4; ++m) _Pragma("unroll") for (int k = 0; k < 2; ++k) dst[m][k] = *(const PG8_LAS bf16x8*)(lds + PG8_SA(b, h) + aoff + m * 2048 + k * 1024); } while (0)
; #define PG8_LDB(dst, b, h) do { _Pragma("unroll") for (int n = 0; n < 2; ++n) _Pragma("unroll") for (int k = 0; k < 2; ++k) dst[n][k] = *(const PG8_LAS bf16x8*)(lds + PG8_SB(b, h) + boff + n * 2048 + k * 1024); } while (0)
; #define PG8_MMA(ai, bj, At, Bt) do { __builtin_amdgcn_s_setprio(1); _Pragma("unroll") for (int m = 0; m < 4; ++m) _Pragma("unroll") for (int n = 0; n < 2; ++n) _Pragma("unroll") for (int k = 0; k < 2; ++k) \
;         acc[ai][bj][m][n] = __builtin_amdgcn_mfma_f32_16x16x32_bf16(Bt[n][k], At[m][k], acc[ai][bj][m][n], 0, 0, 0); __builtin_amdgcn_s_setprio(0); } while (0)
; #define PG8_WAIT_V(n) asm volatile("s_waitcnt vmcnt(" #n ")" ::: "memory")
; #define PG8_WAIT_L(n) asm volatile("s_waitcnt lgkmcnt(" #n ")" ::: "memory")
; template <class Epi, class Sched, bool ALIGN_EPI = false, bool SP2 = false>
; __device__ __forceinline__ void gemm_phase(PG8_LAS unsigned char* lds, const Gemm g, const Sched& S, const Epi& E) {
;     ...
;             const bool last = (t == nt - 2);
;             const char* a1 = cA + (size_t)(t + 1) * kstep;
;             const char* a2 = last ? nA : cA + (size_t)(t + 2) * kstep; const char* b2 = last ? nB : cB + (size_t)(t + 2) * kstep;
;             const char* a3 = a2 + kstep; const char* b3 = b2 + kstep;
;             if (last && has_next) S.a_ready(nxt);
;             if constexpr (SP2) {
;             PG8_LDB(B0, 0, 0); PG8_LDB(B1, 0, 1); PG8_SCHED; PG8_LDA(At, 0, 0); PG8_STAGE(PG8_SA(1, 1), a1 + hstep, voffA);
;             PG8_WAIT_V(8); PG8_WAIT_L(0); PG8_BAR; PG8_MMA(0, 0, At, B0); PG8_MMA(0, 1, At, B1); PG8_BAR; PG8_SCHED;
;             PG8_LDA(At, 0, 1); PG8_STAGE(PG8_SB(0, 0), b2, voffB); PG8_STAGE(PG8_SB(0, 1), b2 + hstep, voffB); PG8_STAGE(PG8_SA(0, 0), a2, voffA);
;             PG8_WAIT_V(8); PG8_WAIT_L(0); PG8_BAR; PG8_MMA(1, 0, At, B0); PG8_MMA(1, 1, At, B1); PG8_BAR; PG8_SCHED;
.LBB0_647:
	s_add_i32 s71, s42, 2
	s_add_u32 s81, s38, 0x80
	s_addc_u32 s43, s39, 0
	s_add_i32 s94, 0, 0x10000
	s_cmp_eq_u32 s24, s42
	s_cselect_b32 s43, s27, s43
	s_cselect_b32 s42, s26, s81
	s_cselect_b32 s93, s91, s45
	s_cselect_b32 s92, s90, s41
	s_add_i32 s81, 0, 0x14000
	v_add_u32_e32 v142, s94, v213
	v_add_u32_e32 v151, s81, v213
	ds_read_b128 v[130:133], v142
	ds_read_b128 v[134:137], v142 offset:1024
	ds_read_b128 v[138:141], v142 offset:2048
	ds_read_b128 v[142:145], v142 offset:3072
	ds_read_b128 v[158:161], v151
	ds_read_b128 v[174:177], v151 offset:1024
	ds_read_b128 v[178:181], v151 offset:2048
	ds_read_b128 v[182:185], v151 offset:3072
	v_lshl_add_u64 v[194:195], s[38:39], 0, v[154:155]
	s_add_i32 m0, s17, 0xc000
	ds_read_b128 v[186:189], v214
	ds_read_b128 v[190:193], v214 offset:1024
	ds_read_b128 v[216:219], v214 offset:2048
	ds_read_b128 v[220:223], v214 offset:3072
	ds_read_b128 v[224:227], v214 offset:4096
	ds_read_b128 v[228:231], v214 offset:5120
	ds_read_b128 v[232:235], v214 offset:6144
	ds_read_b128 v[236:239], v214 offset:7168
	global_load_lds_dwordx4 v[194:195], off
	v_lshl_add_u64 v[194:195], s[38:39], 0, v[156:157]
	s_add_i32 m0, s17, 0xe000
	s_nop 0
	global_load_lds_dwordx4 v[194:195], off
	s_waitcnt vmcnt(8)
	s_waitcnt lgkmcnt(0)
	s_barrier
	s_setprio 1
	s_waitcnt lgkmcnt(0)
	v_mfma_f32_16x16x32_bf16 v[126:129], v[130:133], v[186:189], v[126:129]
	v_mfma_f32_16x16x32_bf16 v[122:125], v[138:141], v[186:189], v[122:125]
	v_mfma_f32_16x16x32_bf16 v[106:109], v[138:141], v[216:219], v[106:109]
	v_mfma_f32_16x16x32_bf16 v[110:113], v[130:133], v[216:219], v[110:113]
	v_mfma_f32_16x16x32_bf16 v[94:97], v[130:133], v[224:227], v[94:97]
	v_mfma_f32_16x16x32_bf16 v[90:93], v[138:141], v[224:227], v[90:93]
	v_mfma_f32_16x16x32_bf16 v[72:75], v[138:141], v[232:235], v[72:75]
	v_mfma_f32_16x16x32_bf16 v[76:79], v[130:133], v[232:235], v[76:79]
	v_mfma_f32_16x16x32_bf16 v[126:129], v[134:137], v[190:193], v[126:129]
	v_mfma_f32_16x16x32_bf16 v[122:125], v[142:145], v[190:193], v[122:125]
	v_mfma_f32_16x16x32_bf16 v[106:109], v[142:145], v[220:223], v[106:109]
	v_mfma_f32_16x16x32_bf16 v[110:113], v[134:137], v[220:223], v[110:113]
	v_mfma_f32_16x16x32_bf16 v[94:97], v[134:137], v[228:231], v[94:97]
	v_mfma_f32_16x16x32_bf16 v[90:93], v[142:145], v[228:231], v[90:93]
	v_mfma_f32_16x16x32_bf16 v[72:75], v[142:145], v[236:239], v[72:75]
	v_mfma_f32_16x16x32_bf16 v[76:79], v[134:137], v[236:239], v[76:79]
	v_mfma_f32_16x16x32_bf16 v[118:121], v[158:161], v[186:189], v[118:121]
	v_mfma_f32_16x16x32_bf16 v[114:117], v[178:181], v[186:189], v[114:117]
	v_mfma_f32_16x16x32_bf16 v[98:101], v[178:181], v[216:219], v[98:101]
	v_mfma_f32_16x16x32_bf16 v[102:105], v[158:161], v[216:219], v[102:105]
	v_mfma_f32_16x16x32_bf16 v[86:89], v[158:161], v[224:227], v[86:89]
	v_mfma_f32_16x16x32_bf16 v[82:85], v[178:181], v[224:227], v[82:85]
	v_mfma_f32_16x16x32_bf16 v[64:67], v[178:181], v[232:235], v[64:67]
	v_mfma_f32_16x16x32_bf16 v[68:71], v[158:161], v[232:235], v[68:71]
	v_mfma_f32_16x16x32_bf16 v[118:121], v[174:177], v[190:193], v[118:121]
	v_mfma_f32_16x16x32_bf16 v[114:117], v[182:185], v[190:193], v[114:117]
	v_mfma_f32_16x16x32_bf16 v[98:101], v[182:185], v[220:223], v[98:101]
	v_mfma_f32_16x16x32_bf16 v[102:105], v[174:177], v[220:223], v[102:105]
	v_mfma_f32_16x16x32_bf16 v[86:89], v[174:177], v[228:231], v[86:89]
	v_mfma_f32_16x16x32_bf16 v[82:85], v[182:185], v[228:231], v[82:85]
	v_mfma_f32_16x16x32_bf16 v[64:67], v[182:185], v[236:239], v[64:67]
	v_mfma_f32_16x16x32_bf16 v[68:71], v[174:177], v[236:239], v[68:71]
	s_setprio 0
	s_barrier
	s_add_i32 s94, s94, s16
	v_lshl_add_u64 v[194:195], s[92:93], 0, v[146:147]
	s_mov_b32 m0, s94
	ds_read_b128 v[186:189], v214 offset:16384
	ds_read_b128 v[190:193], v214 offset:17408
	ds_read_b128 v[216:219], v214 offset:18432
	ds_read_b128 v[220:223], v214 offset:19456
	ds_read_b128 v[224:227], v214 offset:20480
	ds_read_b128 v[228:231], v214 offset:21504
	ds_read_b128 v[232:235], v214 offset:22528
	ds_read_b128 v[236:239], v214 offset:23552
	global_load_lds_dwordx4 v[194:195], off
	s_add_i32 m0, s94, 0x2000
	v_lshl_add_u64 v[240:241], s[92:93], 0, v[148:149]
	s_add_u32 s92, s92, s30
	s_addc_u32 s93, s93, 0
	s_add_i32 s81, s81, s16
	global_load_lds_dwordx4 v[240:241], off
	v_lshl_add_u64 v[242:243], s[92:93], 0, v[146:147]
	s_mov_b32 m0, s81
	v_lshl_add_u64 v[244:245], s[92:93], 0, v[148:149]
	global_load_lds_dwordx4 v[242:243], off
	s_add_i32 m0, s81, 0x2000
	v_lshl_add_u64 v[246:247], s[42:43], 0, v[146:147]
	global_load_lds_dwordx4 v[244:245], off
	s_mov_b32 m0, s17
	v_lshl_add_u64 v[248:249], s[42:43], 0, v[148:149]
	global_load_lds_dwordx4 v[246:247], off
	s_mov_b32 m0, s18
	s_nop 0
	global_load_lds_dwordx4 v[248:249], off
	s_waitcnt vmcnt(8)
	s_waitcnt lgkmcnt(0)
	s_barrier
; #define PG8_STAGE(bufoff, gbase, voff) do { _Pragma("unroll") for (int _i = 0; _i < 2; ++_i) \
;         __builtin_amdgcn_global_load_lds((const unsigned*)((const char*)(gbase) + (voff)[_i]), (PG8_LAS unsigned*)(lds + (bufoff) + ldsw + _i * 8192), 16, 0, 0); } while (0)
; #define PG8_LDA(dst, b, h) do { _Pragma("unroll") for (int m = 0; m < 4; ++m) _Pragma("unroll") for (int k = 0; k < 2; ++k) dst[m][k] = *(const PG8_LAS bf16x8*)(lds + PG8_SA(b, h) + aoff + m * 2048 + k * 1024); } while (0)
; #define PG8_LDB(dst, b, h) do { _Pragma("unroll") for (int n = 0; n < 2; ++n) _Pragma("unroll") for (int k = 0; k < 2; ++k) dst[n][k] = *(const PG8_LAS bf16x8*)(lds + PG8_SB(b, h) + boff + n * 2048 + k * 1024); } while (0)
; #define PG8_MMA(ai, bj, At, Bt) do { __builtin_amdgcn_s_setprio(1); _Pragma("unroll") for (int m = 0; m < 4; ++m) _Pragma("unroll") for (int n = 0; n < 2; ++n) _Pragma("unroll") for (int k = 0; k < 2; ++k) \
;         acc[ai][bj][m][n] = __builtin_amdgcn_mfma_f32_16x16x32_bf16(Bt[n][k], At[m][k], acc[ai][bj][m][n], 0, 0, 0); __builtin_amdgcn_s_setprio(0); } while (0)
; #define PG8_WAIT_V(n) asm volatile("s_waitcnt vmcnt(" #n ")" ::: "memory")
; #define PG8_WAIT_L(n) asm volatile("s_waitcnt lgkmcnt(" #n ")" ::: "memory")
; #define PG8_BAR __builtin_amdgcn_s_barrier()
; #define PG8_SCHED __builtin_amdgcn_sched_barrier(0)
; template <class Epi, class Sched, bool ALIGN_EPI = false, bool SP2 = false>
; __device__ __forceinline__ void gemm_phase(PG8_LAS unsigned char* lds, const Gemm g, const Sched& S, const Epi& E) {
;     ...
;             PG8_WAIT_V(8); PG8_WAIT_L(0); PG8_BAR; PG8_MMA(1, 0, At, B0); PG8_MMA(1, 1, At, B1); PG8_BAR; PG8_SCHED;
;             PG8_LDB(B0, 1, 0); PG8_LDB(B1, 1, 1); PG8_SCHED; PG8_LDA(At, 1, 0); PG8_STAGE(PG8_SA(0, 1), a2 + hstep, voffA);
;             PG8_WAIT_V(8); PG8_WAIT_L(0); PG8_BAR; PG8_MMA(0, 0, At, B0); PG8_MMA(0, 1, At, B1); PG8_BAR; PG8_SCHED;
	s_setprio 1
	s_waitcnt lgkmcnt(0)
	v_mfma_f32_16x16x32_bf16 v[60:63], v[130:133], v[186:189], v[60:63]
	v_mfma_f32_16x16x32_bf16 v[56:59], v[138:141], v[186:189], v[56:59]
	v_mfma_f32_16x16x32_bf16 v[40:43], v[138:141], v[216:219], v[40:43]
	v_mfma_f32_16x16x32_bf16 v[44:47], v[130:133], v[216:219], v[44:47]
	v_mfma_f32_16x16x32_bf16 v[28:31], v[130:133], v[224:227], v[28:31]
	v_mfma_f32_16x16x32_bf16 v[24:27], v[138:141], v[224:227], v[24:27]
	v_mfma_f32_16x16x32_bf16 v[8:11], v[138:141], v[232:235], v[8:11]
	v_mfma_f32_16x16x32_bf16 v[12:15], v[130:133], v[232:235], v[12:15]
	v_mfma_f32_16x16x32_bf16 v[60:63], v[134:137], v[190:193], v[60:63]
	v_mfma_f32_16x16x32_bf16 v[56:59], v[142:145], v[190:193], v[56:59]
	v_mfma_f32_16x16x32_bf16 v[40:43], v[142:145], v[220:223], v[40:43]
	v_mfma_f32_16x16x32_bf16 v[44:47], v[134:137], v[220:223], v[44:47]
	v_mfma_f32_16x16x32_bf16 v[28:31], v[134:137], v[228:231], v[28:31]
	v_mfma_f32_16x16x32_bf16 v[24:27], v[142:145], v[228:231], v[24:27]
	v_mfma_f32_16x16x32_bf16 v[8:11], v[142:145], v[236:239], v[8:11]
	v_mfma_f32_16x16x32_bf16 v[12:15], v[134:137], v[236:239], v[12:15]
	v_mfma_f32_16x16x32_bf16 v[52:55], v[158:161], v[186:189], v[52:55]
	v_mfma_f32_16x16x32_bf16 v[48:51], v[178:181], v[186:189], v[48:51]
	v_mfma_f32_16x16x32_bf16 v[32:35], v[178:181], v[216:219], v[32:35]
	v_mfma_f32_16x16x32_bf16 v[36:39], v[158:161], v[216:219], v[36:39]
	v_mfma_f32_16x16x32_bf16 v[20:23], v[158:161], v[224:227], v[20:23]
	v_mfma_f32_16x16x32_bf16 v[16:19], v[178:181], v[224:227], v[16:19]
	v_mfma_f32_16x16x32_bf16 v[0:3], v[178:181], v[232:235], v[0:3]
	v_mfma_f32_16x16x32_bf16 v[4:7], v[158:161], v[232:235], v[4:7]
	v_mfma_f32_16x16x32_bf16 v[52:55], v[174:177], v[190:193], v[52:55]
	v_mfma_f32_16x16x32_bf16 v[48:51], v[182:185], v[190:193], v[48:51]
	v_mfma_f32_16x16x32_bf16 v[32:35], v[182:185], v[220:223], v[32:35]
	v_mfma_f32_16x16x32_bf16 v[36:39], v[174:177], v[220:223], v[36:39]
	v_mfma_f32_16x16x32_bf16 v[20:23], v[174:177], v[228:231], v[20:23]
	v_mfma_f32_16x16x32_bf16 v[16:19], v[182:185], v[228:231], v[16:19]
	v_mfma_f32_16x16x32_bf16 v[0:3], v[182:185], v[236:239], v[0:3]
	v_mfma_f32_16x16x32_bf16 v[4:7], v[174:177], v[236:239], v[4:7]
	s_setprio 0
	s_barrier
	s_add_i32 s81, 0, 0x18000
	s_add_i32 s92, 0, 0x1c000
	v_add_u32_e32 v142, s81, v213
	v_add_u32_e32 v151, s92, v213
	ds_read_b128 v[130:133], v142
	ds_read_b128 v[134:137], v142 offset:1024
	ds_read_b128 v[138:141], v142 offset:2048
	ds_read_b128 v[142:145], v142 offset:3072
	ds_read_b128 v[158:161], v151
	ds_read_b128 v[174:177], v151 offset:1024
	ds_read_b128 v[178:181], v151 offset:2048
	ds_read_b128 v[182:185], v151 offset:3072
	s_add_u32 s42, s42, s30
	s_addc_u32 s43, s43, 0
	s_mov_b32 m0, s19
	v_lshl_add_u64 v[250:251], s[42:43], 0, v[146:147]
	ds_read_b128 v[186:189], v214 offset:32768
	ds_read_b128 v[190:193], v214 offset:33792
	ds_read_b128 v[216:219], v214 offset:34816
	ds_read_b128 v[220:223], v214 offset:35840
	ds_read_b128 v[224:227], v214 offset:36864
	ds_read_b128 v[228:231], v214 offset:37888
	ds_read_b128 v[232:235], v214 offset:38912
	ds_read_b128 v[236:239], v214 offset:39936
	global_load_lds_dwordx4 v[250:251], off
	v_lshl_add_u64 v[250:251], s[42:43], 0, v[148:149]
	s_mov_b32 m0, s20
	s_nop 0
	global_load_lds_dwordx4 v[250:251], off
	s_waitcnt vmcnt(8)
	s_waitcnt lgkmcnt(0)
	s_barrier
	s_setprio 1
	s_waitcnt lgkmcnt(0)
	v_mfma_f32_16x16x32_bf16 v[126:129], v[130:133], v[186:189], v[126:129]
	v_mfma_f32_16x16x32_bf16 v[122:125], v[138:141], v[186:189], v[122:125]
	v_mfma_f32_16x16x32_bf16 v[106:109], v[138:141], v[216:219], v[106:109]
	v_mfma_f32_16x16x32_bf16 v[110:113], v[130:133], v[216:219], v[110:113]
	v_mfma_f32_16x16x32_bf16 v[94:97], v[130:133], v[224:227], v[94:97]
	v_mfma_f32_16x16x32_bf16 v[90:93], v[138:141], v[224:227], v[90:93]
	v_mfma_f32_16x16x32_bf16 v[72:75], v[138:141], v[232:235], v[72:75]
	v_mfma_f32_16x16x32_bf16 v[76:79], v[130:133], v[232:235], v[76:79]
	v_mfma_f32_16x16x32_bf16 v[126:129], v[134:137], v[190:193], v[126:129]
	v_mfma_f32_16x16x32_bf16 v[122:125], v[142:145], v[190:193], v[122:125]
	v_mfma_f32_16x16x32_bf16 v[106:109], v[142:145], v[220:223], v[106:109]
	v_mfma_f32_16x16x32_bf16 v[110:113], v[134:137], v[220:223], v[110:113]
	v_mfma_f32_16x16x32_bf16 v[94:97], v[134:137], v[228:231], v[94:97]
	v_mfma_f32_16x16x32_bf16 v[90:93], v[142:145], v[228:231], v[90:93]
	v_mfma_f32_16x16x32_bf16 v[72:75], v[142:145], v[236:239], v[72:75]
	v_mfma_f32_16x16x32_bf16 v[76:79], v[134:137], v[236:239], v[76:79]
	v_mfma_f32_16x16x32_bf16 v[118:121], v[158:161], v[186:189], v[118:121]
	v_mfma_f32_16x16x32_bf16 v[114:117], v[178:181], v[186:189], v[114:117]
	v_mfma_f32_16x16x32_bf16 v[98:101], v[178:181], v[216:219], v[98:101]
	v_mfma_f32_16x16x32_bf16 v[102:105], v[158:161], v[216:219], v[102:105]
	v_mfma_f32_16x16x32_bf16 v[86:89], v[158:161], v[224:227], v[86:89]
	v_mfma_f32_16x16x32_bf16 v[82:85], v[178:181], v[224:227], v[82:85]
	v_mfma_f32_16x16x32_bf16 v[64:67], v[178:181], v[232:235], v[64:67]
	v_mfma_f32_16x16x32_bf16 v[68:71], v[158:161], v[232:235], v[68:71]
	v_mfma_f32_16x16x32_bf16 v[118:121], v[174:177], v[190:193], v[118:121]
	v_mfma_f32_16x16x32_bf16 v[114:117], v[182:185], v[190:193], v[114:117]
	v_mfma_f32_16x16x32_bf16 v[98:101], v[182:185], v[220:223], v[98:101]
	v_mfma_f32_16x16x32_bf16 v[102:105], v[174:177], v[220:223], v[102:105]
	v_mfma_f32_16x16x32_bf16 v[86:89], v[174:177], v[228:231], v[86:89]
	v_mfma_f32_16x16x32_bf16 v[82:85], v[182:185], v[228:231], v[82:85]
	v_mfma_f32_16x16x32_bf16 v[64:67], v[182:185], v[236:239], v[64:67]
	v_mfma_f32_16x16x32_bf16 v[68:71], v[174:177], v[236:239], v[68:71]
	s_setprio 0
	s_barrier
; #define PG8_STAGE(bufoff, gbase, voff) do { _Pragma("unroll") for (int _i = 0; _i < 2; ++_i) \
;         __builtin_amdgcn_global_load_lds((const unsigned*)((const char*)(gbase) + (voff)[_i]), (PG8_LAS unsigned*)(lds + (bufoff) + ldsw + _i * 8192), 16, 0, 0); } while (0)
; #define PG8_LDA(dst, b, h) do { _Pragma("unroll") for (int m = 0; m < 4; ++m) _Pragma("unroll") for (int k = 0; k < 2; ++k) dst[m][k] = *(const PG8_LAS bf16x8*)(lds + PG8_SA(b, h) + aoff + m * 2048 + k * 1024); } while (0)
; #define PG8_MMA(ai, bj, At, Bt) do { __builtin_amdgcn_s_setprio(1); _Pragma("unroll") for (int m = 0; m < 4; ++m) _Pragma("unroll") for (int n = 0; n < 2; ++n) _Pragma("unroll") for (int k = 0; k < 2; ++k) \
;         acc[ai][bj][m][n] = __builtin_amdgcn_mfma_f32_16x16x32_bf16(Bt[n][k], At[m][k], acc[ai][bj][m][n], 0, 0, 0); __builtin_amdgcn_s_setprio(0); } while (0)
; #define PG8_WAIT_V(n) asm volatile("s_waitcnt vmcnt(" #n ")" ::: "memory")
; #define PG8_WAIT_L(n) asm volatile("s_waitcnt lgkmcnt(" #n ")" ::: "memory")
; #define PG8_BAR __builtin_amdgcn_s_barrier()
; #define PG8_SCHED __builtin_amdgcn_sched_barrier(0)
; template <class Epi, class Sched, bool ALIGN_EPI = false, bool SP2 = false>
; __device__ __forceinline__ void gemm_phase(PG8_LAS unsigned char* lds, const Gemm g, const Sched& S, const Epi& E) {
;     ...
;             PG8_LDA(At, 1, 1); PG8_STAGE(PG8_SB(1, 0), b3, voffB); PG8_STAGE(PG8_SB(1, 1), b3 + hstep, voffB); PG8_STAGE(PG8_SA(1, 0), a3, voffA);
;             PG8_WAIT_V(8); PG8_WAIT_L(0); PG8_BAR; PG8_MMA(1, 0, At, B0); PG8_MMA(1, 1, At, B1); PG8_BAR; PG8_SCHED;
;     ...
;         if constexpr (ALIGN_EPI) { if (wr == 0) PG8_BAR; }
	s_add_i32 s42, s81, s16
	v_lshl_add_u64 v[194:195], v[194:195], 0, s[0:1]
	s_mov_b32 m0, s42
	ds_read_b128 v[186:189], v214 offset:49152
	ds_read_b128 v[190:193], v214 offset:50176
	ds_read_b128 v[216:219], v214 offset:51200
	ds_read_b128 v[220:223], v214 offset:52224
	ds_read_b128 v[224:227], v214 offset:53248
	ds_read_b128 v[228:231], v214 offset:54272
	ds_read_b128 v[232:235], v214 offset:55296
	ds_read_b128 v[236:239], v214 offset:56320
	global_load_lds_dwordx4 v[194:195], off
	v_lshl_add_u64 v[194:195], v[240:241], 0, s[0:1]
	s_add_i32 m0, s42, 0x2000
	s_add_i32 s42, s92, s16
	global_load_lds_dwordx4 v[194:195], off
	v_lshl_add_u64 v[194:195], v[242:243], 0, s[0:1]
	s_mov_b32 m0, s42
	s_nop 0
	global_load_lds_dwordx4 v[194:195], off
	v_lshl_add_u64 v[194:195], v[244:245], 0, s[0:1]
	s_add_i32 m0, s42, 0x2000
	s_nop 0
	global_load_lds_dwordx4 v[194:195], off
	v_lshl_add_u64 v[194:195], v[246:247], 0, s[0:1]
	s_mov_b32 m0, s8
	s_nop 0
	global_load_lds_dwordx4 v[194:195], off
	v_lshl_add_u64 v[194:195], v[248:249], 0, s[0:1]
	s_mov_b32 m0, s9
	s_nop 0
	global_load_lds_dwordx4 v[194:195], off
	s_waitcnt vmcnt(8)
	s_waitcnt lgkmcnt(0)
	s_barrier
	s_setprio 1
	s_waitcnt lgkmcnt(0)
	v_mfma_f32_16x16x32_bf16 v[60:63], v[130:133], v[186:189], v[60:63]
	v_mfma_f32_16x16x32_bf16 v[56:59], v[138:141], v[186:189], v[56:59]
	v_mfma_f32_16x16x32_bf16 v[40:43], v[138:141], v[216:219], v[40:43]
	v_mfma_f32_16x16x32_bf16 v[44:47], v[130:133], v[216:219], v[44:47]
	v_mfma_f32_16x16x32_bf16 v[28:31], v[130:133], v[224:227], v[28:31]
	v_mfma_f32_16x16x32_bf16 v[24:27], v[138:141], v[224:227], v[24:27]
	v_mfma_f32_16x16x32_bf16 v[8:11], v[138:141], v[232:235], v[8:11]
	v_mfma_f32_16x16x32_bf16 v[12:15], v[130:133], v[232:235], v[12:15]
	v_mfma_f32_16x16x32_bf16 v[60:63], v[134:137], v[190:193], v[60:63]
	v_mfma_f32_16x16x32_bf16 v[56:59], v[142:145], v[190:193], v[56:59]
	v_mfma_f32_16x16x32_bf16 v[40:43], v[142:145], v[220:223], v[40:43]
	v_mfma_f32_16x16x32_bf16 v[44:47], v[134:137], v[220:223], v[44:47]
	v_mfma_f32_16x16x32_bf16 v[28:31], v[134:137], v[228:231], v[28:31]
	v_mfma_f32_16x16x32_bf16 v[24:27], v[142:145], v[228:231], v[24:27]
	v_mfma_f32_16x16x32_bf16 v[8:11], v[142:145], v[236:239], v[8:11]
	v_mfma_f32_16x16x32_bf16 v[12:15], v[134:137], v[236:239], v[12:15]
	v_mfma_f32_16x16x32_bf16 v[52:55], v[158:161], v[186:189], v[52:55]
	v_mfma_f32_16x16x32_bf16 v[48:51], v[178:181], v[186:189], v[48:51]
	v_mfma_f32_16x16x32_bf16 v[32:35], v[178:181], v[216:219], v[32:35]
	v_mfma_f32_16x16x32_bf16 v[36:39], v[158:161], v[216:219], v[36:39]
	v_mfma_f32_16x16x32_bf16 v[20:23], v[158:161], v[224:227], v[20:23]
	v_mfma_f32_16x16x32_bf16 v[16:19], v[178:181], v[224:227], v[16:19]
	v_mfma_f32_16x16x32_bf16 v[0:3], v[178:181], v[232:235], v[0:3]
	v_mfma_f32_16x16x32_bf16 v[4:7], v[158:161], v[232:235], v[4:7]
	v_mfma_f32_16x16x32_bf16 v[52:55], v[174:177], v[190:193], v[52:55]
	v_mfma_f32_16x16x32_bf16 v[48:51], v[182:185], v[190:193], v[48:51]
	v_mfma_f32_16x16x32_bf16 v[32:35], v[182:185], v[220:223], v[32:35]
	v_mfma_f32_16x16x32_bf16 v[36:39], v[174:177], v[220:223], v[36:39]
	v_mfma_f32_16x16x32_bf16 v[20:23], v[174:177], v[228:231], v[20:23]
	v_mfma_f32_16x16x32_bf16 v[16:19], v[182:185], v[228:231], v[16:19]
	v_mfma_f32_16x16x32_bf16 v[0:3], v[182:185], v[236:239], v[0:3]
	v_mfma_f32_16x16x32_bf16 v[4:7], v[174:177], v[236:239], v[4:7]
	s_setprio 0
	s_barrier
	s_add_u32 s38, s38, 0x100
	s_addc_u32 s39, s39, 0
	s_add_u32 s41, s41, 0x100
	s_addc_u32 s45, s45, 0
	s_cmp_ge_u32 s71, s44
	s_mov_b32 s42, s71
	s_cbranch_scc0 .LBB0_647
	s_and_b64 vcc, exec, s[88:89]
	s_cbranch_vccz .LBB0_650
	s_barrier
